# diff-attention unit epilogue: the 8 serialised (load sub-norm weights -> wait -> scale -> store) steps now run with 4 weight loads in flight and counted waits
# baseline (speedup 1.0000x reference)
; __device__ __forceinline__ unsigned cvt_pk_bf16(float lo, float hi) { unsigned r; asm volatile("v_cvt_pk_bf16_f32 %0, %1, %2" : "=v"(r) : "v"(lo), "v"(hi)); return r; }
; template <int NMAP, int VD, bool SWA> ...
;     ...
;         for (int mp = 0; mp < NMAP; ++mp) {
;             if (i == 0 || __builtin_amdgcn_ballot_w64(mx[mp] > 8.0f) != 0ull) {
;                 const float delta = (i == 0) ? mx[mp] : fmaxf(mx[mp], 0.f), alpha = (i == 0) ? 0.f : __builtin_amdgcn_exp2f(-delta);
;                 mrun[mp] += delta; negm[mp] = (f32x4){-mrun[mp], -mrun[mp], -mrun[mp], -mrun[mp]}; lsum[mp] *= alpha;
; #pragma unroll
;                 for (int kt = 0; kt < 4; ++kt) sacc[mp][kt] = sacc[mp][kt] - delta;
; #pragma unroll
;                 for (int et = 0; et < NET; ++et) oacc[mp][et] = oacc[mp][et] * alpha;
;             }
;             float ps = 0.f;
; #pragma unroll
;             for (int kt = 0; kt < 4; ++kt)
; #pragma unroll
;                 for (int r = 0; r < 4; ++r) { const float p = __builtin_amdgcn_exp2f(sacc[mp][kt][r]); sacc[mp][kt][r] = p; ps += p; }
;             lsum[mp] += ps;
; #pragma unroll
;             for (int s2 = 0; s2 < 2; ++s2) {
;                 u32x4 pk; pk.x = cvt_pk_bf16(sacc[mp][2 * s2][0], sacc[mp][2 * s2][1]); pk.y = cvt_pk_bf16(sacc[mp][2 * s2][2], sacc[mp][2 * s2][3]);
;                 pk.z = cvt_pk_bf16(sacc[mp][2 * s2 + 1][0], sacc[mp][2 * s2 + 1][1]); pk.w = cvt_pk_bf16(sacc[mp][2 * s2 + 1][2], sacc[mp][2 * s2 + 1][3]);
;                 pf[mp][s2] = __builtin_bit_cast(bf16x8, pk);
;             }
;         }
; #pragma unroll
;         for (int idx = 0; idx < 2 * NET; ++idx) {
;             const int et = idx % NET, s2 = idx / NET;
;             const bf16x8 cur = va[idx & 3];
;             if (idx + 4 < 2 * NET) ATT_LDV(va[idx & 3], idx + 4);
; #pragma unroll
;             for (int mp = 0; mp < NMAP; ++mp) oacc[mp][et] = __builtin_amdgcn_mfma_f32_16x16x32_bf16(cur, pf[mp][s2], oacc[mp][et], 0, 0, 0);
;         }
;     ...
;         __syncthreads();
.LBB0_138:
	v_add_f32_e32 v110, 0, v110
	v_add_f32_e32 v110, v111, v110
	v_add_f32_e32 v110, v112, v110
	v_add_f32_e32 v110, v113, v110
	v_add_f32_e32 v106, v106, v110
	v_add_f32_e32 v106, v107, v106
	v_exp_f32_e32 v107, v102
	v_exp_f32_e32 v103, v103
	v_exp_f32_e32 v104, v104
	v_exp_f32_e32 v105, v105
	v_add_f32_e32 v102, 0, v107
	v_exp_f32_e32 v94, v94
	v_add_f32_e32 v102, v103, v102
	v_exp_f32_e32 v95, v95
	v_add_f32_e32 v102, v104, v102
	v_exp_f32_e32 v96, v96
	v_add_f32_e32 v102, v105, v102
	v_exp_f32_e32 v97, v97
	v_add_f32_e32 v106, v108, v106
	v_add_f32_e32 v102, v94, v102
	v_exp_f32_e32 v108, v90
	v_add_f32_e32 v106, v109, v106
	v_add_f32_e32 v102, v95, v102
	v_exp_f32_e32 v109, v91
	v_add_f32_e32 v102, v96, v102
	v_exp_f32_e32 v110, v92
	v_add_f32_e32 v102, v97, v102
	v_exp_f32_e32 v111, v93
	v_add_f32_e32 v90, v108, v102
	v_exp_f32_e32 v112, v86
	v_add_f32_e32 v90, v109, v90
	v_exp_f32_e32 v113, v87
	v_add_f32_e32 v106, v115, v106
	v_add_f32_e32 v90, v110, v90
	v_exp_f32_e32 v115, v88
	v_add_f32_e32 v90, v111, v90
	v_exp_f32_e32 v89, v89
	v_add_f32_e32 v86, v112, v90
	v_add_f32_e32 v86, v113, v86
	v_add_f32_e32 v86, v115, v86
	v_add_f32_e32 v86, v89, v86
	v_add_f32_e32 v102, v114, v86
	v_cvt_pk_bf16_f32 v90, v107, v103
	v_cvt_pk_bf16_f32 v91, v104, v105
	v_cvt_pk_bf16_f32 v92, v94, v95
	v_cvt_pk_bf16_f32 v93, v96, v97
	v_cvt_pk_bf16_f32 v86, v108, v109
	v_cvt_pk_bf16_f32 v87, v110, v111
	v_cvt_pk_bf16_f32 v88, v112, v113
	v_cvt_pk_bf16_f32 v89, v115, v89
	ds_read_b64_tr_b16 v[110:111], v0 offset:23168
	ds_read_b64_tr_b16 v[108:109], v0 offset:18560
	ds_read_b64_tr_b16 v[112:113], v0 offset:18592
	ds_read_b64_tr_b16 v[114:115], v0 offset:23200
	v_add_f32_e32 v106, v116, v106
	v_add_f32_e32 v106, v117, v106
	v_add_f32_e32 v106, v118, v106
	v_add_f32_e32 v106, v119, v106
	v_mfma_f32_16x16x32_bf16 v[82:85], v[58:61], v[98:101], v[82:85]
	v_add_f32_e32 v106, v120, v106
	v_add_f32_e32 v106, v121, v106
	v_add_f32_e32 v106, v122, v106
	v_mfma_f32_16x16x32_bf16 v[94:97], v[58:61], v[90:93], v[74:77]
	v_add_f32_e32 v106, v130, v106
	s_lshl_b64 s[8:9], s[20:21], 11
	v_readlane_b32 s10, v252, 55
	v_mfma_f32_16x16x32_bf16 v[74:77], v[14:17], v[98:101], v[78:81]
	v_readlane_b32 s11, v252, 56
	s_add_u32 s3, s10, s8
	s_addc_u32 s9, s11, s9
	v_mfma_f32_16x16x32_bf16 v[58:61], v[14:17], v[90:93], v[70:73]
	ds_read_b64_tr_b16 v[14:15], v0 offset:18624
	ds_read_b64_tr_b16 v[16:17], v0 offset:23232
	s_lshl_b32 s8, s25, 1
	s_add_u32 s8, s3, s8
	v_mfma_f32_16x16x32_bf16 v[54:57], v[6:9], v[98:101], v[54:57]
	s_addc_u32 s9, s9, 0
	v_mfma_f32_16x16x32_bf16 v[66:69], v[6:9], v[90:93], v[66:69]
	ds_read_b64_tr_b16 v[6:7], v0 offset:18656
	ds_read_b64_tr_b16 v[8:9], v0 offset:23264
	ds_read_b64_tr_b16 v[116:117], v0 offset:27648
	ds_read_b64_tr_b16 v[118:119], v0 offset:32256
	s_waitcnt lgkmcnt(8)
	v_mfma_f32_16x16x32_bf16 v[70:73], v[108:111], v[98:101], v[34:37]
	v_mfma_f32_16x16x32_bf16 v[34:37], v[108:111], v[90:93], v[46:49]
	s_nop 2
	ds_read_b64_tr_b16 v[46:47], v0 offset:27680
	ds_read_b64_tr_b16 v[48:49], v0 offset:32288
	ds_read_b64_tr_b16 v[108:109], v0 offset:27712
	ds_read_b64_tr_b16 v[110:111], v0 offset:32320
	ds_read_b64_tr_b16 v[120:121], v0 offset:27744
	ds_read_b64_tr_b16 v[122:123], v0 offset:32352
	v_mfma_f32_16x16x32_bf16 v[50:53], v[2:5], v[98:101], v[50:53]
	ds_read_b64_tr_b16 v[124:125], v0 offset:27776
	ds_read_b64_tr_b16 v[126:127], v0 offset:32384
	v_mfma_f32_16x16x32_bf16 v[62:65], v[2:5], v[90:93], v[62:65]
	s_waitcnt lgkmcnt(14)
	v_mfma_f32_16x16x32_bf16 v[38:41], v[112:115], v[98:101], v[38:41]
	v_mfma_f32_16x16x32_bf16 v[42:45], v[112:115], v[90:93], v[42:45]
	s_waitcnt lgkmcnt(12)
	v_mfma_f32_16x16x32_bf16 v[78:81], v[14:17], v[98:101], v[30:33]
	v_mfma_f32_16x16x32_bf16 v[112:115], v[14:17], v[90:93], v[26:29]
	s_waitcnt lgkmcnt(10)
	v_mfma_f32_16x16x32_bf16 v[98:101], v[6:9], v[98:101], v[22:25]
	v_mfma_f32_16x16x32_bf16 v[90:93], v[6:9], v[90:93], v[18:21]
	s_waitcnt lgkmcnt(8)
	v_mfma_f32_16x16x32_bf16 v[2:5], v[116:119], v[10:13], v[82:85]
	s_nop 2
	ds_read_b64_tr_b16 v[82:83], v0 offset:27808
	ds_read_b64_tr_b16 v[84:85], v0 offset:32416
	s_waitcnt lgkmcnt(8)
	v_mfma_f32_16x16x32_bf16 v[18:21], v[46:49], v[86:89], v[58:61]
	s_nop 2
	ds_read_b64_tr_b16 v[58:59], v0 offset:27840
	ds_read_b64_tr_b16 v[60:61], v0 offset:32448
	s_waitcnt lgkmcnt(8)
	v_mfma_f32_16x16x32_bf16 v[22:25], v[108:111], v[10:13], v[54:57]
	s_nop 2
	ds_read_b64_tr_b16 v[54:55], v0 offset:27872
	ds_read_b64_tr_b16 v[56:57], v0 offset:32480
	ds_bpermute_b32 v0, v179, v106
	s_waitcnt lgkmcnt(0)
	v_mfma_f32_16x16x32_bf16 v[14:17], v[46:49], v[10:13], v[74:77]
	s_barrier
; template <int NMAP, int VD, bool SWA> ...
;     ...
;     float lt[NMAP];
; #pragma unroll
;     for (int mp = 0; mp < NMAP; ++mp) { float v = lsum[mp]; v += __shfl_xor(v, 16); v += __shfl_xor(v, 32); lt[mp] = v; }
;     bf16_t* orow = Op + (size_t)(16 * w + fr) * DM + 4 * fq;
;     if constexpr (!SWA) {
;         const float inv0 = 1.0f / lt[0], inv1 = lam / lt[1];
;         float ss = 0.f;
; #pragma unroll
;         for (int et = 0; et < NET; ++et)
; #pragma unroll
;             for (int r = 0; r < 4; ++r) { const float o = oacc[0][et][r] * inv0 - oacc[1][et][r] * inv1; oacc[0][et][r] = o; ss += o * o; }
;         ss += __shfl_xor(ss, 16); ss += __shfl_xor(ss, 32);
	v_add_f32_e32 v0, v106, v0
	v_mfma_f32_16x16x32_bf16 v[26:29], v[108:111], v[86:89], v[66:69]
	v_mfma_f32_16x16x32_bf16 v[30:33], v[120:123], v[10:13], v[50:53]
	v_mfma_f32_16x16x32_bf16 v[50:53], v[124:127], v[10:13], v[70:73]
	v_mfma_f32_16x16x32_bf16 v[66:69], v[82:85], v[10:13], v[38:41]
	v_mfma_f32_16x16x32_bf16 v[74:77], v[58:61], v[10:13], v[78:81]
	v_mfma_f32_16x16x32_bf16 v[78:81], v[54:57], v[10:13], v[98:101]
	ds_bpermute_b32 v10, v180, v0
	s_waitcnt lgkmcnt(0)
	v_add_f32_e32 v0, v0, v10
	ds_bpermute_b32 v10, v179, v102
	v_mfma_f32_16x16x32_bf16 v[46:49], v[120:123], v[86:89], v[62:65]
	s_waitcnt lgkmcnt(0)
	v_add_f32_e32 v10, v102, v10
	ds_bpermute_b32 v11, v180, v10
	v_mfma_f32_16x16x32_bf16 v[62:65], v[124:127], v[86:89], v[34:37]
	s_waitcnt lgkmcnt(0)
	v_add_f32_e32 v10, v10, v11
	v_div_scale_f32 v11, s[10:11], v0, v0, 1.0
	v_rcp_f32_e32 v12, v11
	v_mfma_f32_16x16x32_bf16 v[6:9], v[116:119], v[86:89], v[94:97]
	v_fma_f32 v13, -v11, v12, 1.0
	v_fmac_f32_e32 v12, v13, v12
	v_div_scale_f32 v13, vcc, 1.0, v0, 1.0
	v_mul_f32_e32 v34, v13, v12
	v_fma_f32 v35, -v11, v34, v13
	v_fmac_f32_e32 v34, v35, v12
	v_fma_f32 v11, -v11, v34, v13
	v_div_fmas_f32 v11, v11, v12, v34
	v_div_fixup_f32 v0, v11, v0, 1.0
	v_div_scale_f32 v11, s[10:11], v10, v10, v159
	v_rcp_f32_e32 v12, v11
	v_mfma_f32_16x16x32_bf16 v[70:73], v[82:85], v[86:89], v[42:45]
	v_fma_f32 v13, -v11, v12, 1.0
	v_fmac_f32_e32 v12, v13, v12
	v_div_scale_f32 v13, vcc, v159, v10, v159
	v_mul_f32_e32 v34, v13, v12
	v_fma_f32 v35, -v11, v34, v13
	v_fmac_f32_e32 v34, v35, v12
	v_fma_f32 v11, -v11, v34, v13
	v_div_fmas_f32 v11, v11, v12, v34
	v_div_fixup_f32 v82, v11, v10, v159
	v_pk_mul_f32 v[6:7], v[6:7], v[82:83] op_sel_hi:[1,0]
	v_mfma_f32_16x16x32_bf16 v[58:61], v[58:61], v[86:89], v[112:115]
	v_fma_f32 v40, v2, v0, -v6
	v_fma_f32 v41, v3, v0, -v7
	v_pk_mul_f32 v[6:7], v[8:9], v[82:83] op_sel_hi:[1,0]
	v_pk_mul_f32 v[2:3], v[40:41], v[40:41]
	v_pk_fma_f32 v[42:43], v[4:5], v[0:1], v[6:7] op_sel_hi:[1,0,1] neg_lo:[0,0,1] neg_hi:[0,0,1]
	v_pk_mul_f32 v[6:7], v[18:19], v[82:83] op_sel_hi:[1,0]
	v_mfma_f32_16x16x32_bf16 v[54:57], v[54:57], v[86:89], v[90:93]
	v_fma_f32 v36, v14, v0, -v6
	v_fma_f32 v37, v15, v0, -v7
	v_pk_mul_f32 v[6:7], v[20:21], v[82:83] op_sel_hi:[1,0]
	v_pk_mul_f32 v[4:5], v[42:43], v[42:43]
	v_pk_fma_f32 v[38:39], v[16:17], v[0:1], v[6:7] op_sel_hi:[1,0,1] neg_lo:[0,0,1] neg_hi:[0,0,1]
	v_pk_mul_f32 v[6:7], v[26:27], v[82:83] op_sel_hi:[1,0]
	s_nop 1
	v_pk_mul_f32 v[8:9], v[56:57], v[82:83] op_sel_hi:[1,0]
	v_pk_fma_f32 v[34:35], v[22:23], v[0:1], v[6:7] op_sel_hi:[1,0,1] neg_lo:[0,0,1] neg_hi:[0,0,1]
	v_pk_mul_f32 v[6:7], v[28:29], v[82:83] op_sel_hi:[1,0]
	v_pk_fma_f32 v[8:9], v[80:81], v[0:1], v[8:9] op_sel_hi:[1,0,1] neg_lo:[0,0,1] neg_hi:[0,0,1]
	v_pk_fma_f32 v[28:29], v[24:25], v[0:1], v[6:7] op_sel_hi:[1,0,1] neg_lo:[0,0,1] neg_hi:[0,0,1]
	v_pk_mul_f32 v[6:7], v[46:47], v[82:83] op_sel_hi:[1,0]
	v_pk_mul_f32 v[14:15], v[36:37], v[36:37]
	v_pk_fma_f32 v[24:25], v[30:31], v[0:1], v[6:7] op_sel_hi:[1,0,1] neg_lo:[0,0,1] neg_hi:[0,0,1]
	v_pk_mul_f32 v[6:7], v[48:49], v[82:83] op_sel_hi:[1,0]
	v_pk_mul_f32 v[84:85], v[38:39], v[38:39]
	v_pk_fma_f32 v[26:27], v[32:33], v[0:1], v[6:7] op_sel_hi:[1,0,1] neg_lo:[0,0,1] neg_hi:[0,0,1]
	v_pk_mul_f32 v[6:7], v[62:63], v[82:83] op_sel_hi:[1,0]
	v_pk_mul_f32 v[86:87], v[34:35], v[34:35]
	v_pk_fma_f32 v[20:21], v[50:51], v[0:1], v[6:7] op_sel_hi:[1,0,1] neg_lo:[0,0,1] neg_hi:[0,0,1]
	v_pk_mul_f32 v[6:7], v[64:65], v[82:83] op_sel_hi:[1,0]
	v_pk_mul_f32 v[88:89], v[28:29], v[28:29]
	v_pk_fma_f32 v[22:23], v[52:53], v[0:1], v[6:7] op_sel_hi:[1,0,1] neg_lo:[0,0,1] neg_hi:[0,0,1]
	v_pk_mul_f32 v[6:7], v[70:71], v[82:83] op_sel_hi:[1,0]
	v_pk_mul_f32 v[30:31], v[24:25], v[24:25]
	v_pk_fma_f32 v[16:17], v[66:67], v[0:1], v[6:7] op_sel_hi:[1,0,1] neg_lo:[0,0,1] neg_hi:[0,0,1]
	v_pk_mul_f32 v[6:7], v[72:73], v[82:83] op_sel_hi:[1,0]
	v_pk_mul_f32 v[32:33], v[26:27], v[26:27]
	v_pk_fma_f32 v[18:19], v[68:69], v[0:1], v[6:7] op_sel_hi:[1,0,1] neg_lo:[0,0,1] neg_hi:[0,0,1]
	v_pk_mul_f32 v[6:7], v[58:59], v[82:83] op_sel_hi:[1,0]
	v_pk_mul_f32 v[46:47], v[20:21], v[20:21]
	v_pk_fma_f32 v[10:11], v[74:75], v[0:1], v[6:7] op_sel_hi:[1,0,1] neg_lo:[0,0,1] neg_hi:[0,0,1]
	v_pk_mul_f32 v[6:7], v[60:61], v[82:83] op_sel_hi:[1,0]
	v_pk_mul_f32 v[48:49], v[22:23], v[22:23]
	v_pk_fma_f32 v[12:13], v[76:77], v[0:1], v[6:7] op_sel_hi:[1,0,1] neg_lo:[0,0,1] neg_hi:[0,0,1]
	v_pk_mul_f32 v[6:7], v[54:55], v[82:83] op_sel_hi:[1,0]
	v_pk_mul_f32 v[50:51], v[16:17], v[16:17]
	v_pk_fma_f32 v[6:7], v[78:79], v[0:1], v[6:7] op_sel_hi:[1,0,1] neg_lo:[0,0,1] neg_hi:[0,0,1]
	v_add_f32_e32 v0, v2, v3
	v_add_f32_e32 v0, v4, v0
	v_add_f32_e32 v0, v5, v0
	v_add_f32_e32 v0, v14, v0
	v_add_f32_e32 v0, v15, v0
	v_add_f32_e32 v0, v84, v0
	v_add_f32_e32 v0, v85, v0
	v_add_f32_e32 v0, v86, v0
	v_add_f32_e32 v0, v87, v0
	v_add_f32_e32 v0, v88, v0
	v_add_f32_e32 v0, v89, v0
	v_add_f32_e32 v0, v30, v0
	v_add_f32_e32 v0, v31, v0
	v_add_f32_e32 v0, v32, v0
	v_add_f32_e32 v0, v33, v0
	v_add_f32_e32 v0, v46, v0
	v_add_f32_e32 v0, v47, v0
	v_add_f32_e32 v0, v48, v0
	v_add_f32_e32 v0, v49, v0
	v_add_f32_e32 v0, v50, v0
	v_pk_mul_f32 v[52:53], v[18:19], v[18:19]
	v_add_f32_e32 v0, v51, v0
	v_add_f32_e32 v0, v52, v0
	v_pk_mul_f32 v[58:59], v[10:11], v[10:11]
	v_add_f32_e32 v0, v53, v0
	v_add_f32_e32 v0, v58, v0
	v_pk_mul_f32 v[60:61], v[12:13], v[12:13]
	v_add_f32_e32 v0, v59, v0
	v_add_f32_e32 v0, v60, v0
	v_pk_mul_f32 v[54:55], v[6:7], v[6:7]
	v_add_f32_e32 v0, v61, v0
	v_add_f32_e32 v0, v54, v0
	v_pk_mul_f32 v[56:57], v[8:9], v[8:9]
	v_add_f32_e32 v0, v55, v0
	v_lshlrev_b64 v[44:45], 11, v[160:161]
	v_add_f32_e32 v0, v56, v0
	v_add_f32_e32 v4, v57, v0
	v_lshl_add_u64 v[2:3], s[8:9], 0, v[44:45]
	v_lshlrev_b32_e32 v0, 1, v163
	v_lshl_add_u64 v[14:15], v[2:3], 0, v[0:1]
	ds_bpermute_b32 v0, v179, v4
	v_lshlrev_b32_e32 v44, 2, v163
	s_mov_b64 s[8:9], 0
	s_waitcnt lgkmcnt(0)
; __device__ __forceinline__ unsigned cvt_pk_bf16(float lo, float hi) { unsigned r; asm volatile("v_cvt_pk_bf16_f32 %0, %1, %2" : "=v"(r) : "v"(lo), "v"(hi)); return r; }
; template <int NMAP, int VD, bool SWA> ...
;     ...
;         ss += __shfl_xor(ss, 16); ss += __shfl_xor(ss, 32);
;         const float rstd = rsqrtf(ss * (1.0f / VD) + EPSV) * post_scale;
; #pragma unroll
;         for (int et = 0; et < NET; ++et) { const f32x4 g = *(const f32x4*)(gsub + 16 * et + 4 * fq); const f32x4 v = oacc[0][et] * rstd * g;
;             *(u32x2*)(orow + 16 * et) = (u32x2){cvt_pk_bf16(v[0], v[1]), cvt_pk_bf16(v[2], v[3])}; }
	v_add_f32_e32 v0, v4, v0
	ds_bpermute_b32 v2, v180, v0
	s_waitcnt lgkmcnt(0)
	v_add_f32_e32 v0, v0, v2
	v_fmamk_f32 v0, v0, 0x3c000000, v185
	v_cmp_gt_f32_e32 vcc, s33, v0
	v_mul_f32_e32 v2, 0x4b800000, v0
	s_nop 0
	v_cndmask_b32_e32 v0, v0, v2, vcc
	v_rsq_f32_e32 v0, v0
	s_nop 0
	v_mul_f32_e32 v2, 0x45800000, v0
	v_cndmask_b32_e32 v0, v0, v2, vcc
	global_load_dwordx4 v[236:239], v44, s[30:31]
	global_load_dwordx4 v[240:243], v44, s[30:31] offset:64
	global_load_dwordx4 v[244:247], v44, s[30:31] offset:128
	global_load_dwordx4 v[248:251], v44, s[30:31] offset:192
	v_mul_f32_e32 v0, v172, v0
	v_pk_mul_f32 v[30:31], v[40:41], v[0:1] op_sel_hi:[1,0]
	v_pk_mul_f32 v[32:33], v[42:43], v[0:1] op_sel_hi:[1,0]
	v_pk_mul_f32 v[28:29], v[28:29], v[0:1] op_sel_hi:[1,0]
	v_pk_mul_f32 v[24:25], v[24:25], v[0:1] op_sel_hi:[1,0]
	v_pk_mul_f32 v[26:27], v[26:27], v[0:1] op_sel_hi:[1,0]
	v_pk_mul_f32 v[20:21], v[20:21], v[0:1] op_sel_hi:[1,0]
	v_pk_mul_f32 v[22:23], v[22:23], v[0:1] op_sel_hi:[1,0]
	v_pk_mul_f32 v[16:17], v[16:17], v[0:1] op_sel_hi:[1,0]
	v_pk_mul_f32 v[18:19], v[18:19], v[0:1] op_sel_hi:[1,0]
	v_pk_mul_f32 v[10:11], v[10:11], v[0:1] op_sel_hi:[1,0]
	v_pk_mul_f32 v[12:13], v[12:13], v[0:1] op_sel_hi:[1,0]
	v_pk_mul_f32 v[6:7], v[6:7], v[0:1] op_sel_hi:[1,0]
	v_pk_mul_f32 v[8:9], v[8:9], v[0:1] op_sel_hi:[1,0]
	s_waitcnt vmcnt(3)
	v_pk_mul_f32 v[2:3], v[236:237], v[30:31]
	v_pk_mul_f32 v[4:5], v[238:239], v[32:33]
	global_load_dwordx4 v[236:239], v44, s[30:31] offset:256
	v_cvt_pk_bf16_f32 v2, v2, v3
	v_pk_mul_f32 v[30:31], v[36:37], v[0:1] op_sel_hi:[1,0]
	v_cvt_pk_bf16_f32 v3, v4, v5
	global_store_dwordx2 v[14:15], v[2:3], off offset:512
	v_pk_mul_f32 v[32:33], v[38:39], v[0:1] op_sel_hi:[1,0]
	s_waitcnt vmcnt(4)
	v_pk_mul_f32 v[2:3], v[240:241], v[30:31]
	v_pk_mul_f32 v[4:5], v[242:243], v[32:33]
	global_load_dwordx4 v[240:243], v44, s[30:31] offset:320
	v_cvt_pk_bf16_f32 v2, v2, v3
	v_pk_mul_f32 v[30:31], v[34:35], v[0:1] op_sel_hi:[1,0]
	v_cvt_pk_bf16_f32 v3, v4, v5
	global_store_dwordx2 v[14:15], v[2:3], off offset:544
	s_waitcnt vmcnt(5)
	v_pk_mul_f32 v[2:3], v[244:245], v[30:31]
	v_pk_mul_f32 v[4:5], v[246:247], v[28:29]
	global_load_dwordx4 v[244:247], v44, s[30:31] offset:384
	v_cvt_pk_bf16_f32 v2, v2, v3
	s_nop 0
	v_cvt_pk_bf16_f32 v3, v4, v5
	global_store_dwordx2 v[14:15], v[2:3], off offset:576
	s_waitcnt vmcnt(6)
	v_pk_mul_f32 v[2:3], v[248:249], v[24:25]
	v_pk_mul_f32 v[4:5], v[250:251], v[26:27]
	global_load_dwordx4 v[248:251], v44, s[30:31] offset:448
	v_cvt_pk_bf16_f32 v2, v2, v3
	s_nop 0
	v_cvt_pk_bf16_f32 v3, v4, v5
	global_store_dwordx2 v[14:15], v[2:3], off offset:608
	s_waitcnt vmcnt(7)
	v_pk_mul_f32 v[2:3], v[236:237], v[20:21]
	v_pk_mul_f32 v[4:5], v[238:239], v[22:23]
	v_cvt_pk_bf16_f32 v2, v2, v3
	s_nop 0
	v_cvt_pk_bf16_f32 v3, v4, v5
	global_store_dwordx2 v[14:15], v[2:3], off offset:640
	s_waitcnt vmcnt(6)
	v_pk_mul_f32 v[2:3], v[240:241], v[16:17]
	v_pk_mul_f32 v[4:5], v[242:243], v[18:19]
	v_cvt_pk_bf16_f32 v2, v2, v3
	s_nop 0
	v_cvt_pk_bf16_f32 v3, v4, v5
	global_store_dwordx2 v[14:15], v[2:3], off offset:672
	s_waitcnt vmcnt(5)
	v_pk_mul_f32 v[2:3], v[244:245], v[10:11]
	v_pk_mul_f32 v[4:5], v[246:247], v[12:13]
	v_cvt_pk_bf16_f32 v2, v2, v3
	s_nop 0
	v_cvt_pk_bf16_f32 v3, v4, v5
	global_store_dwordx2 v[14:15], v[2:3], off offset:704
	s_waitcnt vmcnt(4)
	v_pk_mul_f32 v[2:3], v[248:249], v[6:7]
	v_pk_mul_f32 v[4:5], v[250:251], v[8:9]
	v_cvt_pk_bf16_f32 v2, v2, v3
	s_nop 0
	v_cvt_pk_bf16_f32 v3, v4, v5
	global_store_dwordx2 v[14:15], v[2:3], off offset:736
	s_barrier
